# v11 + soft seams at 5 GEMM->GEMM group seams: consumer starts once every workgroup finished the producer's first unit (early counter), full arrival checked at the consumer's 2nd/3rd unit header
# speedup vs baseline: 1.0101x; 1.0101x over previous
;     __host__ __device__ bool next(int i, Unit& u) const {
;         const int L = i * G + c; if (L >= nwg) return false;
;         const int nig = WGM * nN, gid = L / nig, fm = gid * WGM, gsz = (nM - fm) < WGM ? (nM - fm) : WGM;
;         u.pm = fm + ((L % nig) % gsz); u.pn = (L % nig) / gsz; return true;
; template <class Epi, class Sched, bool ALIGN_EPI = false, bool SP2 = false>
; __device__ __forceinline__ void gemm_phase(PG8_LAS unsigned char* lds, const Gemm g, const Sched& S, const Epi& E) {
;     ...
;         const bool has_next = S.next(ui + 1, nxt);
;         const char* nA = has_next ? (const char*)g.A + (size_t)nxt.pm * tstep : cA; const char* nB = has_next ? (const char*)g.Bt + (size_t)nxt.pn * tstep : cB;
.LBB0_238:
	s_add_i32 s62, s62, 1
	s_cmp_eq_u32 s62, 2
	s_cbranch_scc0 .Lss_p_2
	s_waitcnt vmcnt(0)
	s_lshl_b32 s101, s33, 8
	s_add_u32 s101, s101, 0x1400
	s_add_u32 s101, s54, s101
	v_mov_b32_e32 v248, s101
	s_addc_u32 s101, s55, 0
	v_mov_b32_e32 v249, s101
	v_mov_b32_e32 v250, 1
	s_mov_b64 exec, 1
	global_atomic_add v[248:249], v250, off offset:16
	s_mov_b64 exec, -1
.Lss_p_2:
	s_mul_i32 s4, s62, s94
	s_add_i32 s4, s4, s95
	s_cmp_lt_i32 s4, 64
	s_cselect_b64 s[46:47], -1, 0
	s_cmp_gt_i32 s4, 63
	s_cbranch_scc1 .LBB0_240
	s_ashr_i32 s5, s4, 31
	s_lshr_b32 s5, s5, 28
	s_add_i32 s5, s4, s5
	s_ashr_i32 s50, s5, 4
	s_and_b32 s5, s5, 0xfff0
	s_sub_i32 s4, s4, s5
	s_bfe_i32 s5, s4, 0x80000
	s_bfe_u32 s5, s5, 0x2000d
	s_add_i32 s5, s4, s5
	s_bfe_i32 s51, s5, 0x80000
	s_and_b32 s5, s5, 0xfc
	s_sub_i32 s4, s4, s5
	s_lshl_b32 s50, s50, 2
	s_sext_i32_i16 s51, s51
	s_sext_i32_i8 s4, s4
	s_add_i32 s80, s50, s4
	s_ashr_i32 s79, s51, 2

; __device__ __forceinline__ unsigned xb_ld(unsigned* p)              { return __hip_atomic_load(p, __ATOMIC_RELAXED, __HIP_MEMORY_SCOPE_AGENT); }
; __device__ __forceinline__ unsigned xb_add(unsigned* p, unsigned v) { return __hip_atomic_fetch_add(p, v, __ATOMIC_RELAXED, __HIP_MEMORY_SCOPE_AGENT); }
; #define XB_SPIN(cond, bar) do { unsigned _sp = 0; while (cond) { __builtin_amdgcn_s_sleep(1); \
;     if ((++_sp & 255u) == 0u) { if (xb_ld(&(bar)[XB_TMO])) break; if (_sp > XB_SPIN_CAP) { atomicAdd(&(bar)[XB_TMO], 1u); break; } } } } while (0)
; __device__ __forceinline__ void xcd_barrier(const XcdBarrier& b) {
;     asm volatile("s_waitcnt vmcnt(0)" ::: "memory");
;     __syncthreads();
;     if (threadIdx.x == 0) {
;         unsigned* bar = b.bar;
;         __builtin_amdgcn_s_waitcnt(0);
;         unsigned nloc = b.st[0], nx = b.st[1];
;         if (nloc == 0u) { xcd_barrier_complete(bar, b.x, b.gsz, nloc, nx); b.st[0] = nloc; b.st[1] = nx; }
;         const unsigned old = xb_add(&bar[XB_XSUB(b.x)], 1u);
;         const unsigned gen = old / nloc;
;         if (old + 1u == (gen + 1u) * nloc) {
;             __builtin_amdgcn_fence(__ATOMIC_RELEASE, "agent");
;             asm volatile("s_waitcnt vmcnt(0)" ::: "memory");
;             const unsigned og = xb_add(&bar[XB_TOP], 1u);
;             const unsigned tg = og / nx;
;             if (og + 1u == (tg + 1u) * nx) xb_add(&bar[XB_TOPGEN], 1u);
;             else XB_SPIN(xb_ld(&bar[XB_TOPGEN]) == tg, bar);
;             __builtin_amdgcn_fence(__ATOMIC_ACQUIRE, "agent");
;             xb_add(&bar[XB_XGEN(b.x)], 1u);
;             asm volatile("s_waitcnt vmcnt(0)" ::: "memory");
;         } else {
;             XB_SPIN(xb_ld(&bar[XB_XGEN(b.x)]) == gen, bar);
;             __builtin_amdgcn_fence(__ATOMIC_ACQUIRE, "agent");
;             asm volatile("s_waitcnt vmcnt(0)" ::: "memory");
;         }
.LBB0_283:
	s_waitcnt lgkmcnt(0)
	v_cmp_ne_u32_e32 vcc, 1, v0
	s_cbranch_vccnz .Lxslow_2
	s_lshl_b32 s4, s33, 8
	s_add_u32 s4, s54, s4
	s_addc_u32 s5, s55, 0
	s_add_i32 s100, s100, 1
	v_mov_b32_e32 v1, 0x1000
	v_mov_b32_e32 v3, 1
	global_atomic_add v0, v1, v3, s[4:5] offset:1024 sc0
	v_lshlrev_b32_e32 v2, 3, v2
	s_mov_b32 s101, 0
	s_waitcnt vmcnt(0)
	buffer_inv sc1
	v_mov_b32_e32 v0, 0
	v_mov_b32_e32 v1, 0x1010

;     __host__ __device__ bool next(int i, Unit& u) const {
;         const int L = i * G + c; if (L >= nwg) return false;
;         const int nig = WGM * nN, gid = L / nig, fm = gid * WGM, gsz = (nM - fm) < WGM ? (nM - fm) : WGM;
;         u.pm = fm + ((L % nig) % gsz); u.pn = (L % nig) / gsz; return true;
; template <class Epi, class Sched, bool ALIGN_EPI = false, bool SP2 = false>
; __device__ __forceinline__ void gemm_phase(PG8_LAS unsigned char* lds, const Gemm g, const Sched& S, const Epi& E) {
;     ...
;         const bool has_next = S.next(ui + 1, nxt);
;         const char* nA = has_next ? (const char*)g.A + (size_t)nxt.pm * tstep : cA; const char* nB = has_next ? (const char*)g.Bt + (size_t)nxt.pn * tstep : cB;
.LBB0_322:
	s_add_i32 s37, s37, 1
	s_cmp_eq_u32 s97, 0
	s_cbranch_scc0 .Lss_c_2
	s_cmp_eq_u32 s37, 2
	s_cbranch_scc0 .Lss_c_2
	v_mov_b32_e32 v252, s92
	ds_read_b32 v251, v252
	ds_read_b32 v253, v252 offset:4
	s_lshl_b32 s101, s33, 8
	s_add_u32 s101, s101, 0x1400
	s_add_u32 s101, s54, s101
	v_mov_b32_e32 v248, s101
	s_addc_u32 s101, s55, 0
	v_mov_b32_e32 v249, s101
	global_load_dword v250, v[248:249], off sc1
	s_waitcnt vmcnt(0) lgkmcnt(0)
	v_readfirstlane_b32 s101, v253
	s_cmp_eq_u32 s101, 1
	s_cbranch_scc0 .Lss_c_2
	v_mul_lo_u32 v251, v251, s100
	v_mov_b32_e32 v254, 0
.Lss_spin_2:
	v_sub_u32_e32 v250, v250, v251
	v_add_u32_e32 v254, 1, v254
	s_nop 0
	v_readfirstlane_b32 s101, v250
	s_cmp_lt_i32 s101, 0
	s_cbranch_scc0 .Lss_done_2
	v_readfirstlane_b32 s101, v254
	s_cmp_gt_u32 s101, 0x800
	s_cbranch_scc1 .Lss_done_2
	s_sleep 1
	global_load_dword v250, v[248:249], off sc1
	s_waitcnt vmcnt(0)
	s_branch .Lss_spin_2
.Lss_done_2:
.Lss_c_2:
	s_mul_i32 s5, s37, s94
	s_add_i32 s5, s5, s95
	s_cmpk_lt_i32 s5, 0xa0
	s_cselect_b64 s[64:65], -1, 0
	s_cmpk_gt_i32 s5, 0x9f
	s_cbranch_scc1 .LBB0_324
	s_mul_hi_i32 s60, s5, 0x66666667
	s_lshr_b32 s61, s60, 31
	s_ashr_i32 s60, s60, 4
	s_add_i32 s60, s60, s61
	s_lshl_b32 s61, s60, 2
	s_mul_i32 s60, s60, 40
	s_sub_i32 s5, s5, s60
	s_bfe_i32 s60, s5, 0x80000
	s_bfe_u32 s60, s60, 0x2000d
	s_add_i32 s60, s5, s60
	s_bfe_i32 s62, s60, 0x80000
	s_and_b32 s60, s60, 0xfc
	s_sub_i32 s5, s5, s60
	s_sext_i32_i16 s62, s62
	s_sext_i32_i8 s5, s5
	s_add_i32 s60, s61, s5
	s_ashr_i32 s62, s62, 2

;     __host__ __device__ bool next(int i, Unit& u) const {
;         const int L = i * G + c; if (L >= nwg) return false;
;         const int nig = WGM * nN, gid = L / nig, fm = gid * WGM, gsz = (nM - fm) < WGM ? (nM - fm) : WGM;
;         u.pm = fm + ((L % nig) % gsz); u.pn = (L % nig) / gsz; return true;
; template <class Epi, class Sched, bool ALIGN_EPI = false, bool SP2 = false>
; __device__ __forceinline__ void gemm_phase(PG8_LAS unsigned char* lds, const Gemm g, const Sched& S, const Epi& E) {
;     ...
;         const bool has_next = S.next(ui + 1, nxt);
;         const char* nA = has_next ? (const char*)g.A + (size_t)nxt.pm * tstep : cA; const char* nB = has_next ? (const char*)g.Bt + (size_t)nxt.pn * tstep : cB;
.LBB0_579:
	s_add_i32 s39, s39, 1
	s_cmp_eq_u32 s39, 2
	s_cbranch_scc0 .Lss_p_7
	s_waitcnt vmcnt(0)
	s_lshl_b32 s101, s33, 8
	s_add_u32 s101, s101, 0x1400
	s_add_u32 s101, s54, s101
	v_mov_b32_e32 v248, s101
	s_addc_u32 s101, s55, 0
	v_mov_b32_e32 v249, s101
	v_mov_b32_e32 v250, 1
	s_mov_b64 exec, 1
	global_atomic_add v[248:249], v250, off offset:20
	s_mov_b64 exec, -1
.Lss_p_7:
	s_mul_i32 s56, s39, s94
	s_add_i32 s56, s56, s95
	s_cmp_lt_i32 s56, 64
	s_cselect_b64 s[74:75], -1, 0
	s_cmp_gt_i32 s56, 63
	s_cbranch_scc1 .LBB0_581
	s_ashr_i32 s57, s56, 31
	s_lshr_b32 s57, s57, 28
	s_add_i32 s57, s56, s57
	s_ashr_i32 s58, s57, 4
	s_and_b32 s57, s57, 0xfff0
	s_sub_i32 s56, s56, s57
	s_bfe_i32 s57, s56, 0x80000
	s_bfe_u32 s57, s57, 0x2000d
	s_add_i32 s57, s56, s57
	s_bfe_i32 s59, s57, 0x80000
	s_and_b32 s57, s57, 0xfc
	s_sub_i32 s56, s56, s57
	s_lshl_b32 s58, s58, 2
	s_sext_i32_i16 s59, s59
	s_sext_i32_i8 s56, s56
	s_add_i32 s70, s58, s56
	s_ashr_i32 s72, s59, 2

; __device__ __forceinline__ unsigned xb_ld(unsigned* p)              { return __hip_atomic_load(p, __ATOMIC_RELAXED, __HIP_MEMORY_SCOPE_AGENT); }
; __device__ __forceinline__ unsigned xb_add(unsigned* p, unsigned v) { return __hip_atomic_fetch_add(p, v, __ATOMIC_RELAXED, __HIP_MEMORY_SCOPE_AGENT); }
; #define XB_SPIN(cond, bar) do { unsigned _sp = 0; while (cond) { __builtin_amdgcn_s_sleep(1); \
;     if ((++_sp & 255u) == 0u) { if (xb_ld(&(bar)[XB_TMO])) break; if (_sp > XB_SPIN_CAP) { atomicAdd(&(bar)[XB_TMO], 1u); break; } } } } while (0)
; __device__ __forceinline__ void xcd_barrier(const XcdBarrier& b) {
;     asm volatile("s_waitcnt vmcnt(0)" ::: "memory");
;     __syncthreads();
;     if (threadIdx.x == 0) {
;         unsigned* bar = b.bar;
;         __builtin_amdgcn_s_waitcnt(0);
;         unsigned nloc = b.st[0], nx = b.st[1];
;         if (nloc == 0u) { xcd_barrier_complete(bar, b.x, b.gsz, nloc, nx); b.st[0] = nloc; b.st[1] = nx; }
;         const unsigned old = xb_add(&bar[XB_XSUB(b.x)], 1u);
;         const unsigned gen = old / nloc;
;         if (old + 1u == (gen + 1u) * nloc) {
;             __builtin_amdgcn_fence(__ATOMIC_RELEASE, "agent");
;             asm volatile("s_waitcnt vmcnt(0)" ::: "memory");
;             const unsigned og = xb_add(&bar[XB_TOP], 1u);
;             const unsigned tg = og / nx;
;             if (og + 1u == (tg + 1u) * nx) xb_add(&bar[XB_TOPGEN], 1u);
;             else XB_SPIN(xb_ld(&bar[XB_TOPGEN]) == tg, bar);
;             __builtin_amdgcn_fence(__ATOMIC_ACQUIRE, "agent");
;             xb_add(&bar[XB_XGEN(b.x)], 1u);
;             asm volatile("s_waitcnt vmcnt(0)" ::: "memory");
;         } else {
;             XB_SPIN(xb_ld(&bar[XB_XGEN(b.x)]) == gen, bar);
;             __builtin_amdgcn_fence(__ATOMIC_ACQUIRE, "agent");
;             asm volatile("s_waitcnt vmcnt(0)" ::: "memory");
;         }
.LBB0_620:
	s_waitcnt lgkmcnt(0)
	v_cmp_ne_u32_e32 vcc, 1, v0
	s_cbranch_vccnz .Lxslow_7
	s_lshl_b32 s2, s33, 8
	s_add_u32 s6, s54, s2
	s_addc_u32 s7, s55, 0
	s_add_i32 s100, s100, 1
	v_mov_b32_e32 v1, 0x1000
	v_mov_b32_e32 v3, 1
	global_atomic_add v0, v1, v3, s[6:7] offset:1024 sc0
	v_lshlrev_b32_e32 v2, 3, v2
	s_mov_b32 s101, 0
	s_waitcnt vmcnt(0)
	buffer_inv sc1
	v_mov_b32_e32 v0, 0
	v_mov_b32_e32 v1, 0x1014

;     __host__ __device__ bool next(int i, Unit& u) const {
;         const int L = i * G + c; if (L >= nwg) return false;
;         const int nig = WGM * nN, gid = L / nig, fm = gid * WGM, gsz = (nM - fm) < WGM ? (nM - fm) : WGM;
;         u.pm = fm + ((L % nig) % gsz); u.pn = (L % nig) / gsz; return true;
; template <class Epi, class Sched, bool ALIGN_EPI = false, bool SP2 = false>
; __device__ __forceinline__ void gemm_phase(PG8_LAS unsigned char* lds, const Gemm g, const Sched& S, const Epi& E) {
;     ...
;         const bool has_next = S.next(ui + 1, nxt);
;         const char* nA = has_next ? (const char*)g.A + (size_t)nxt.pm * tstep : cA; const char* nB = has_next ? (const char*)g.Bt + (size_t)nxt.pn * tstep : cB;
.LBB0_657:
	s_add_i32 s30, s30, 1
	s_cmp_eq_u32 s97, 0
	s_cbranch_scc0 .Lss_c_7
	s_cmp_eq_u32 s30, 2
	s_cbranch_scc0 .Lss_c1_7
	s_lshl_b32 s101, s33, 8
	s_add_u32 s101, s101, 0x1400
	s_add_u32 s101, s54, s101
	v_mov_b32_e32 v248, s101
	s_addc_u32 s101, s55, 0
	v_mov_b32_e32 v249, s101
	global_load_dword v250, v[248:249], off sc1
.Lss_c1_7:
	s_cmp_eq_u32 s30, 3
	s_cbranch_scc0 .Lss_c_7
	v_mov_b32_e32 v252, s92
	ds_read_b32 v251, v252
	ds_read_b32 v253, v252 offset:4
	s_waitcnt lgkmcnt(0)
	v_readfirstlane_b32 s101, v253
	s_cmp_eq_u32 s101, 1
	s_cbranch_scc0 .Lss_c_7
	v_mul_lo_u32 v251, v251, s100
	v_mov_b32_e32 v254, 0

;     __host__ __device__ bool next(int i, Unit& u) const {
;         const int L = i * G + c; if (L >= nwg) return false;
;         const int nig = WGM * nN, gid = L / nig, fm = gid * WGM, gsz = (nM - fm) < WGM ? (nM - fm) : WGM;
;         u.pm = fm + ((L % nig) % gsz); u.pn = (L % nig) / gsz; return true;
; template <class Epi, class Sched, bool ALIGN_EPI = false, bool SP2 = false>
; __device__ __forceinline__ void gemm_phase(PG8_LAS unsigned char* lds, const Gemm g, const Sched& S, const Epi& E) {
;     ...
;         const bool has_next = S.next(ui + 1, nxt);
;         const char* nA = has_next ? (const char*)g.A + (size_t)nxt.pm * tstep : cA; const char* nB = has_next ? (const char*)g.Bt + (size_t)nxt.pn * tstep : cB;
.Lss_done_7:
.Lss_c_7:
	s_mul_i32 s5, s30, s94
	s_add_i32 s5, s5, s95
	s_cmpk_lt_i32 s5, 0x160
	s_cselect_b64 s[78:79], -1, 0
	s_cmpk_gt_i32 s5, 0x15f
	s_cbranch_scc1 .LBB0_659
	s_mul_hi_i32 s58, s5, 0x2e8ba2e9
	s_lshr_b32 s59, s58, 31
	s_ashr_i32 s58, s58, 4
	s_add_i32 s58, s58, s59
	s_lshl_b32 s59, s58, 2
	s_mulk_i32 s58, 0x58
	s_sub_i32 s5, s5, s58
	s_bfe_i32 s58, s5, 0x80000
	s_bfe_u32 s58, s58, 0x2000d
	s_add_i32 s58, s5, s58
	s_bfe_i32 s60, s58, 0x80000
	s_and_b32 s58, s58, 0xfc
	s_sub_i32 s5, s5, s58
	s_sext_i32_i16 s60, s60
	s_sext_i32_i8 s5, s5
	s_add_i32 s70, s59, s5
	s_ashr_i32 s72, s60, 2

;     __host__ __device__ bool next(int i, Unit& u) const {
;         const int L = i * G + c; if (L >= nwg) return false;
;         const int nig = WGM * nN, gid = L / nig, fm = gid * WGM, gsz = (nM - fm) < WGM ? (nM - fm) : WGM;
;         u.pm = fm + ((L % nig) % gsz); u.pn = (L % nig) / gsz; return true;
; template <class Epi, class Sched, bool ALIGN_EPI = false, bool SP2 = false>
; __device__ __forceinline__ void gemm_phase(PG8_LAS unsigned char* lds, const Gemm g, const Sched& S, const Epi& E) {
;     ...
;         const bool has_next = S.next(ui + 1, nxt);
;         const char* nA = has_next ? (const char*)g.A + (size_t)nxt.pm * tstep : cA; const char* nB = has_next ? (const char*)g.Bt + (size_t)nxt.pn * tstep : cB;
.LBB0_723:
	s_add_i32 s39, s39, 1
	s_cmp_eq_u32 s39, 2
	s_cbranch_scc0 .Lss_p_9
	s_waitcnt vmcnt(0)
	s_lshl_b32 s101, s33, 8
	s_add_u32 s101, s101, 0x1400
	s_add_u32 s101, s54, s101
	v_mov_b32_e32 v248, s101
	s_addc_u32 s101, s55, 0
	v_mov_b32_e32 v249, s101
	v_mov_b32_e32 v250, 1
	s_mov_b64 exec, 1
	global_atomic_add v[248:249], v250, off offset:24
	s_mov_b64 exec, -1
.Lss_p_9:
	s_mul_i32 s6, s39, s94
	s_add_i32 s6, s6, s95
	s_cmp_lt_i32 s6, 64
	s_cselect_b64 s[72:73], -1, 0
	s_cmp_gt_i32 s6, 63
	s_cbranch_scc1 .LBB0_725
	s_ashr_i32 s2, s6, 31
	s_lshr_b32 s2, s2, 28
	s_add_i32 s2, s6, s2
	s_ashr_i32 s7, s2, 4
	s_and_b32 s2, s2, 0xfff0
	s_sub_i32 s2, s6, s2
	s_bfe_i32 s6, s2, 0x80000
	s_bfe_u32 s6, s6, 0x2000d
	s_add_i32 s6, s2, s6
	s_bfe_i32 s11, s6, 0x80000
	s_and_b32 s6, s6, 0xfc
	s_sub_i32 s2, s2, s6
	s_lshl_b32 s7, s7, 2
	s_sext_i32_i16 s11, s11
	s_sext_i32_i8 s2, s2
	s_add_i32 s2, s7, s2
	s_ashr_i32 s11, s11, 2

; __device__ __forceinline__ unsigned xb_ld(unsigned* p)              { return __hip_atomic_load(p, __ATOMIC_RELAXED, __HIP_MEMORY_SCOPE_AGENT); }
; __device__ __forceinline__ unsigned xb_add(unsigned* p, unsigned v) { return __hip_atomic_fetch_add(p, v, __ATOMIC_RELAXED, __HIP_MEMORY_SCOPE_AGENT); }
; #define XB_SPIN(cond, bar) do { unsigned _sp = 0; while (cond) { __builtin_amdgcn_s_sleep(1); \
;     if ((++_sp & 255u) == 0u) { if (xb_ld(&(bar)[XB_TMO])) break; if (_sp > XB_SPIN_CAP) { atomicAdd(&(bar)[XB_TMO], 1u); break; } } } } while (0)
; __device__ __forceinline__ void xcd_barrier(const XcdBarrier& b) {
;     asm volatile("s_waitcnt vmcnt(0)" ::: "memory");
;     __syncthreads();
;     if (threadIdx.x == 0) {
;         unsigned* bar = b.bar;
;         __builtin_amdgcn_s_waitcnt(0);
;         unsigned nloc = b.st[0], nx = b.st[1];
;         if (nloc == 0u) { xcd_barrier_complete(bar, b.x, b.gsz, nloc, nx); b.st[0] = nloc; b.st[1] = nx; }
;         const unsigned old = xb_add(&bar[XB_XSUB(b.x)], 1u);
;         const unsigned gen = old / nloc;
;         if (old + 1u == (gen + 1u) * nloc) {
;             __builtin_amdgcn_fence(__ATOMIC_RELEASE, "agent");
;             asm volatile("s_waitcnt vmcnt(0)" ::: "memory");
;             const unsigned og = xb_add(&bar[XB_TOP], 1u);
;             const unsigned tg = og / nx;
;             if (og + 1u == (tg + 1u) * nx) xb_add(&bar[XB_TOPGEN], 1u);
;             else XB_SPIN(xb_ld(&bar[XB_TOPGEN]) == tg, bar);
;             __builtin_amdgcn_fence(__ATOMIC_ACQUIRE, "agent");
;             xb_add(&bar[XB_XGEN(b.x)], 1u);
;             asm volatile("s_waitcnt vmcnt(0)" ::: "memory");
;         } else {
;             XB_SPIN(xb_ld(&bar[XB_XGEN(b.x)]) == gen, bar);
;             __builtin_amdgcn_fence(__ATOMIC_ACQUIRE, "agent");
;             asm volatile("s_waitcnt vmcnt(0)" ::: "memory");
;         }
.LBB0_768:
	s_waitcnt lgkmcnt(0)
	v_cmp_ne_u32_e32 vcc, 1, v0
	s_cbranch_vccnz .Lxslow_9
	s_lshl_b32 s2, s33, 8
	s_add_u32 s6, s54, s2
	s_addc_u32 s7, s55, 0
	s_add_i32 s100, s100, 1
	v_mov_b32_e32 v1, 0x1000
	v_mov_b32_e32 v3, 1
	global_atomic_add v0, v1, v3, s[6:7] offset:1024 sc0
	v_lshlrev_b32_e32 v2, 3, v2
	s_mov_b32 s101, 0
	s_waitcnt vmcnt(0)
	buffer_inv sc1
	v_mov_b32_e32 v0, 0
	v_mov_b32_e32 v1, 0x1018

;     __host__ __device__ bool next(int i, Unit& u) const {
;         const int L = i * G + c; if (L >= nwg) return false;
;         const int nig = WGM * nN, gid = L / nig, fm = gid * WGM, gsz = (nM - fm) < WGM ? (nM - fm) : WGM;
;         u.pm = fm + ((L % nig) % gsz); u.pn = (L % nig) / gsz; return true;
; template <class Epi, class Sched, bool ALIGN_EPI = false, bool SP2 = false>
; __device__ __forceinline__ void gemm_phase(PG8_LAS unsigned char* lds, const Gemm g, const Sched& S, const Epi& E) {
;     ...
;         const bool has_next = S.next(ui + 1, nxt);
;         const char* nA = has_next ? (const char*)g.A + (size_t)nxt.pm * tstep : cA; const char* nB = has_next ? (const char*)g.Bt + (size_t)nxt.pn * tstep : cB;
.LBB0_871:
	s_add_i32 s39, s39, 1
	s_cmp_eq_u32 s39, 2
	s_cbranch_scc0 .Lss_p_11
	s_waitcnt vmcnt(0)
	s_lshl_b32 s101, s33, 8
	s_add_u32 s101, s101, 0x1400
	s_add_u32 s101, s54, s101
	v_mov_b32_e32 v248, s101
	s_addc_u32 s101, s55, 0
	v_mov_b32_e32 v249, s101
	v_mov_b32_e32 v250, 1
	s_mov_b64 exec, 1
	global_atomic_add v[248:249], v250, off offset:28
	s_mov_b64 exec, -1
.Lss_p_11:
	s_mul_i32 s6, s39, s94
	s_add_i32 s6, s6, s95
	s_cmp_lt_i32 s6, 64
	s_cselect_b64 s[72:73], -1, 0
	s_cmp_gt_i32 s6, 63
	s_cbranch_scc1 .LBB0_873
	s_ashr_i32 s2, s6, 31
	s_lshr_b32 s2, s2, 28
	s_add_i32 s2, s6, s2
	s_ashr_i32 s3, s2, 4
	s_and_b32 s2, s2, 0xfff0
	s_sub_i32 s2, s6, s2
	s_bfe_i32 s6, s2, 0x80000
	s_bfe_u32 s6, s6, 0x2000d
	s_add_i32 s6, s2, s6
	s_bfe_i32 s7, s6, 0x80000
	s_and_b32 s6, s6, 0xfc
	s_sub_i32 s2, s2, s6
	s_lshl_b32 s3, s3, 2
	s_sext_i32_i16 s7, s7
	s_sext_i32_i8 s2, s2
	s_add_i32 s3, s3, s2
	s_ashr_i32 s2, s7, 2

; __device__ __forceinline__ unsigned xb_ld(unsigned* p)              { return __hip_atomic_load(p, __ATOMIC_RELAXED, __HIP_MEMORY_SCOPE_AGENT); }
; __device__ __forceinline__ unsigned xb_add(unsigned* p, unsigned v) { return __hip_atomic_fetch_add(p, v, __ATOMIC_RELAXED, __HIP_MEMORY_SCOPE_AGENT); }
; #define XB_SPIN(cond, bar) do { unsigned _sp = 0; while (cond) { __builtin_amdgcn_s_sleep(1); \
;     if ((++_sp & 255u) == 0u) { if (xb_ld(&(bar)[XB_TMO])) break; if (_sp > XB_SPIN_CAP) { atomicAdd(&(bar)[XB_TMO], 1u); break; } } } } while (0)
; __device__ __forceinline__ void xcd_barrier(const XcdBarrier& b) {
;     asm volatile("s_waitcnt vmcnt(0)" ::: "memory");
;     __syncthreads();
;     if (threadIdx.x == 0) {
;         unsigned* bar = b.bar;
;         __builtin_amdgcn_s_waitcnt(0);
;         unsigned nloc = b.st[0], nx = b.st[1];
;         if (nloc == 0u) { xcd_barrier_complete(bar, b.x, b.gsz, nloc, nx); b.st[0] = nloc; b.st[1] = nx; }
;         const unsigned old = xb_add(&bar[XB_XSUB(b.x)], 1u);
;         const unsigned gen = old / nloc;
;         if (old + 1u == (gen + 1u) * nloc) {
;             __builtin_amdgcn_fence(__ATOMIC_RELEASE, "agent");
;             asm volatile("s_waitcnt vmcnt(0)" ::: "memory");
;             const unsigned og = xb_add(&bar[XB_TOP], 1u);
;             const unsigned tg = og / nx;
;             if (og + 1u == (tg + 1u) * nx) xb_add(&bar[XB_TOPGEN], 1u);
;             else XB_SPIN(xb_ld(&bar[XB_TOPGEN]) == tg, bar);
;             __builtin_amdgcn_fence(__ATOMIC_ACQUIRE, "agent");
;             xb_add(&bar[XB_XGEN(b.x)], 1u);
;             asm volatile("s_waitcnt vmcnt(0)" ::: "memory");
;         } else {
;             XB_SPIN(xb_ld(&bar[XB_XGEN(b.x)]) == gen, bar);
;             __builtin_amdgcn_fence(__ATOMIC_ACQUIRE, "agent");
;             asm volatile("s_waitcnt vmcnt(0)" ::: "memory");
;         }
.LBB0_916:
	s_waitcnt lgkmcnt(0)
	v_cmp_ne_u32_e32 vcc, 1, v0
	s_cbranch_vccnz .Lxslow_11
	s_lshl_b32 s2, s33, 8
	s_add_u32 s6, s54, s2
	s_addc_u32 s7, s55, 0
	s_add_i32 s100, s100, 1
	v_mov_b32_e32 v1, 0x1000
	v_mov_b32_e32 v3, 1
	global_atomic_add v0, v1, v3, s[6:7] offset:1024 sc0
	v_lshlrev_b32_e32 v2, 3, v2
	s_mov_b32 s101, 0
	s_waitcnt vmcnt(0)
	buffer_inv sc1
	v_mov_b32_e32 v0, 0
	v_mov_b32_e32 v1, 0x101c

;     __host__ __device__ bool next(int i, Unit& u) const {
;         const int L = i * G + c; if (L >= nwg) return false;
;         const int nig = WGM * nN, gid = L / nig, fm = gid * WGM, gsz = (nM - fm) < WGM ? (nM - fm) : WGM;
;         u.pm = fm + ((L % nig) % gsz); u.pn = (L % nig) / gsz; return true;
; template <class Epi, class Sched, bool ALIGN_EPI = false, bool SP2 = false>
; __device__ __forceinline__ void gemm_phase(PG8_LAS unsigned char* lds, const Gemm g, const Sched& S, const Epi& E) {
;     ...
;         const bool has_next = S.next(ui + 1, nxt);
;         const char* nA = has_next ? (const char*)g.A + (size_t)nxt.pm * tstep : cA; const char* nB = has_next ? (const char*)g.Bt + (size_t)nxt.pn * tstep : cB;
.LBB0_955:
	s_add_i32 s30, s30, 1
	s_cmp_eq_u32 s97, 0
	s_cbranch_scc0 .Lss_c_11
	s_cmp_eq_u32 s30, 2
	s_cbranch_scc0 .Lss_c_11
	v_mov_b32_e32 v252, s92
	ds_read_b32 v251, v252
	ds_read_b32 v253, v252 offset:4
	s_lshl_b32 s101, s33, 8
	s_add_u32 s101, s101, 0x1400
	s_add_u32 s101, s54, s101
	v_mov_b32_e32 v248, s101
	s_addc_u32 s101, s55, 0
	v_mov_b32_e32 v249, s101
	global_load_dword v250, v[248:249], off sc1
	s_waitcnt vmcnt(0) lgkmcnt(0)
	v_readfirstlane_b32 s101, v253
	s_cmp_eq_u32 s101, 1
	s_cbranch_scc0 .Lss_c_11
	v_mul_lo_u32 v251, v251, s100
	v_mov_b32_e32 v254, 0

;     __host__ __device__ bool next(int i, Unit& u) const {
;         const int L = i * G + c; if (L >= nwg) return false;
;         const int nig = WGM * nN, gid = L / nig, fm = gid * WGM, gsz = (nM - fm) < WGM ? (nM - fm) : WGM;
;         u.pm = fm + ((L % nig) % gsz); u.pn = (L % nig) / gsz; return true;
; template <class Epi, class Sched, bool ALIGN_EPI = false, bool SP2 = false>
; __device__ __forceinline__ void gemm_phase(PG8_LAS unsigned char* lds, const Gemm g, const Sched& S, const Epi& E) {
;     ...
;         const bool has_next = S.next(ui + 1, nxt);
;         const char* nA = has_next ? (const char*)g.A + (size_t)nxt.pm * tstep : cA; const char* nB = has_next ? (const char*)g.Bt + (size_t)nxt.pn * tstep : cB;
.Lss_done_11:
.Lss_c_11:
	s_mul_i32 s7, s30, s94
	s_add_i32 s7, s7, s95
	s_cmpk_lt_i32 s7, 0xa0
	s_cselect_b64 s[78:79], -1, 0
	s_cmpk_gt_i32 s7, 0x9f
	s_cbranch_scc1 .LBB0_957
	s_mul_hi_i32 s58, s7, 0x66666667
	s_lshr_b32 s59, s58, 31
	s_ashr_i32 s58, s58, 4
	s_add_i32 s58, s58, s59
	s_lshl_b32 s59, s58, 2
	s_mul_i32 s58, s58, 40
	s_sub_i32 s7, s7, s58
	s_bfe_i32 s58, s7, 0x80000
	s_bfe_u32 s58, s58, 0x2000d
	s_add_i32 s58, s7, s58
	s_bfe_i32 s60, s58, 0x80000
	s_and_b32 s58, s58, 0xfc
	s_sub_i32 s7, s7, s58
	s_sext_i32_i16 s60, s60
	s_sext_i32_i8 s7, s7
	s_add_i32 s74, s59, s7
	s_ashr_i32 s76, s60, 2

;     __host__ __device__ bool next(int i, Unit& u) const {
;         const int L = i * G + c; if (L >= nwg) return false;
;         const int nig = WGM * nN, gid = L / nig, fm = gid * WGM, gsz = (nM - fm) < WGM ? (nM - fm) : WGM;
;         u.pm = fm + ((L % nig) % gsz); u.pn = (L % nig) / gsz; return true;
; template <class Epi, class Sched, bool ALIGN_EPI = false, bool SP2 = false>
; __device__ __forceinline__ void gemm_phase(PG8_LAS unsigned char* lds, const Gemm g, const Sched& S, const Epi& E) {
;     ...
;         const bool has_next = S.next(ui + 1, nxt);
;         const char* nA = has_next ? (const char*)g.A + (size_t)nxt.pm * tstep : cA; const char* nB = has_next ? (const char*)g.Bt + (size_t)nxt.pn * tstep : cB;
.LBB0_1212:
	s_add_i32 s37, s37, 1
	s_cmp_eq_u32 s37, 2
	s_cbranch_scc0 .Lss_p_16
	s_waitcnt vmcnt(0)
	s_lshl_b32 s101, s33, 8
	s_add_u32 s101, s101, 0x1400
	s_add_u32 s101, s54, s101
	v_mov_b32_e32 v248, s101
	s_addc_u32 s101, s55, 0
	v_mov_b32_e32 v249, s101
	v_mov_b32_e32 v250, 1
	s_mov_b64 exec, 1
	global_atomic_add v[248:249], v250, off offset:32
	s_mov_b64 exec, -1
.Lss_p_16:
	s_mul_i32 s17, s37, s94
	s_add_i32 s17, s17, s95
	s_cmp_lt_i32 s17, 64
	s_cselect_b64 s[42:43], -1, 0
	s_cmp_gt_i32 s17, 63
	s_cbranch_scc1 .LBB0_1214
	s_ashr_i32 s16, s17, 31
	s_lshr_b32 s16, s16, 28
	s_add_i32 s16, s17, s16
	s_ashr_i32 s18, s16, 4
	s_and_b32 s16, s16, 0xfff0
	s_sub_i32 s16, s17, s16
	s_bfe_i32 s17, s16, 0x80000
	s_bfe_u32 s17, s17, 0x2000d
	s_add_i32 s17, s16, s17
	s_bfe_i32 s19, s17, 0x80000
	s_and_b32 s17, s17, 0xfc
	s_sub_i32 s16, s16, s17
	s_lshl_b32 s18, s18, 2
	s_sext_i32_i16 s19, s19
	s_sext_i32_i8 s16, s16
	s_add_i32 s16, s18, s16
	s_ashr_i32 s18, s19, 2

; __device__ __forceinline__ unsigned xb_ld(unsigned* p)              { return __hip_atomic_load(p, __ATOMIC_RELAXED, __HIP_MEMORY_SCOPE_AGENT); }
; __device__ __forceinline__ unsigned xb_add(unsigned* p, unsigned v) { return __hip_atomic_fetch_add(p, v, __ATOMIC_RELAXED, __HIP_MEMORY_SCOPE_AGENT); }
; #define XB_SPIN(cond, bar) do { unsigned _sp = 0; while (cond) { __builtin_amdgcn_s_sleep(1); \
;     if ((++_sp & 255u) == 0u) { if (xb_ld(&(bar)[XB_TMO])) break; if (_sp > XB_SPIN_CAP) { atomicAdd(&(bar)[XB_TMO], 1u); break; } } } } while (0)
; __device__ __forceinline__ void xcd_barrier(const XcdBarrier& b) {
;     asm volatile("s_waitcnt vmcnt(0)" ::: "memory");
;     __syncthreads();
;     if (threadIdx.x == 0) {
;         unsigned* bar = b.bar;
;         __builtin_amdgcn_s_waitcnt(0);
;         unsigned nloc = b.st[0], nx = b.st[1];
;         if (nloc == 0u) { xcd_barrier_complete(bar, b.x, b.gsz, nloc, nx); b.st[0] = nloc; b.st[1] = nx; }
;         const unsigned old = xb_add(&bar[XB_XSUB(b.x)], 1u);
;         const unsigned gen = old / nloc;
;         if (old + 1u == (gen + 1u) * nloc) {
;             __builtin_amdgcn_fence(__ATOMIC_RELEASE, "agent");
;             asm volatile("s_waitcnt vmcnt(0)" ::: "memory");
;             const unsigned og = xb_add(&bar[XB_TOP], 1u);
;             const unsigned tg = og / nx;
;             if (og + 1u == (tg + 1u) * nx) xb_add(&bar[XB_TOPGEN], 1u);
;             else XB_SPIN(xb_ld(&bar[XB_TOPGEN]) == tg, bar);
;             __builtin_amdgcn_fence(__ATOMIC_ACQUIRE, "agent");
;             xb_add(&bar[XB_XGEN(b.x)], 1u);
;             asm volatile("s_waitcnt vmcnt(0)" ::: "memory");
;         } else {
;             XB_SPIN(xb_ld(&bar[XB_XGEN(b.x)]) == gen, bar);
;             __builtin_amdgcn_fence(__ATOMIC_ACQUIRE, "agent");
;             asm volatile("s_waitcnt vmcnt(0)" ::: "memory");
;         }
.LBB0_1253:
	s_waitcnt lgkmcnt(0)
	v_cmp_ne_u32_e32 vcc, 1, v0
	s_cbranch_vccnz .Lxslow_16
	s_lshl_b32 s4, s33, 8
	s_add_u32 s4, s54, s4
	s_addc_u32 s5, s55, 0
	s_add_i32 s100, s100, 1
	v_mov_b32_e32 v1, 0x1000
	v_mov_b32_e32 v3, 1
	global_atomic_add v0, v1, v3, s[4:5] offset:1024 sc0
	v_lshlrev_b32_e32 v2, 3, v2
	s_mov_b32 s101, 0
	s_waitcnt vmcnt(0)
	buffer_inv sc1
	v_mov_b32_e32 v0, 0
	v_mov_b32_e32 v1, 0x1020

;     __host__ __device__ bool next(int i, Unit& u) const {
;         const int L = i * G + c; if (L >= nwg) return false;
;         const int nig = WGM * nN, gid = L / nig, fm = gid * WGM, gsz = (nM - fm) < WGM ? (nM - fm) : WGM;
;         u.pm = fm + ((L % nig) % gsz); u.pn = (L % nig) / gsz; return true;
; template <class Epi, class Sched, bool ALIGN_EPI = false, bool SP2 = false>
; __device__ __forceinline__ void gemm_phase(PG8_LAS unsigned char* lds, const Gemm g, const Sched& S, const Epi& E) {
;     ...
;         const bool has_next = S.next(ui + 1, nxt);
;         const char* nA = has_next ? (const char*)g.A + (size_t)nxt.pm * tstep : cA; const char* nB = has_next ? (const char*)g.Bt + (size_t)nxt.pn * tstep : cB;
.LBB0_1290:
	s_add_i32 s37, s37, 1
	s_cmp_eq_u32 s97, 0
	s_cbranch_scc0 .Lss_c_16
	s_cmp_eq_u32 s37, 2
	s_cbranch_scc0 .Lss_c1_16
	s_lshl_b32 s101, s33, 8
	s_add_u32 s101, s101, 0x1400
	s_add_u32 s101, s54, s101
	v_mov_b32_e32 v248, s101
	s_addc_u32 s101, s55, 0
	v_mov_b32_e32 v249, s101
	global_load_dword v250, v[248:249], off sc1
.Lss_c1_16:
	s_cmp_eq_u32 s37, 3
	s_cbranch_scc0 .Lss_c_16
	v_mov_b32_e32 v252, s92
	ds_read_b32 v251, v252
	ds_read_b32 v253, v252 offset:4
	s_waitcnt lgkmcnt(0)
	v_readfirstlane_b32 s101, v253
	s_cmp_eq_u32 s101, 1
	s_cbranch_scc0 .Lss_c_16
	v_mul_lo_u32 v251, v251, s100
	v_mov_b32_e32 v254, 0

;     __host__ __device__ bool next(int i, Unit& u) const {
;         const int L = i * G + c; if (L >= nwg) return false;
;         const int nig = WGM * nN, gid = L / nig, fm = gid * WGM, gsz = (nM - fm) < WGM ? (nM - fm) : WGM;
;         u.pm = fm + ((L % nig) % gsz); u.pn = (L % nig) / gsz; return true;
; template <class Epi, class Sched, bool ALIGN_EPI = false, bool SP2 = false>
; __device__ __forceinline__ void gemm_phase(PG8_LAS unsigned char* lds, const Gemm g, const Sched& S, const Epi& E) {
;     ...
;         const bool has_next = S.next(ui + 1, nxt);
;         const char* nA = has_next ? (const char*)g.A + (size_t)nxt.pm * tstep : cA; const char* nB = has_next ? (const char*)g.Bt + (size_t)nxt.pn * tstep : cB;
.Lss_done_16:
.Lss_c_16:
	s_mul_i32 s3, s37, s94
	s_add_i32 s3, s3, s95
	s_cmpk_lt_i32 s3, 0x160
	s_cselect_b64 s[46:47], -1, 0
	s_cmpk_gt_i32 s3, 0x15f
	s_cbranch_scc1 .LBB0_1292
	s_mul_hi_i32 s16, s3, 0x2e8ba2e9
	s_lshr_b32 s17, s16, 31
	s_ashr_i32 s16, s16, 4
	s_add_i32 s16, s16, s17
	s_lshl_b32 s17, s16, 2
	s_mulk_i32 s16, 0x58
	s_sub_i32 s3, s3, s16
	s_bfe_i32 s16, s3, 0x80000
	s_bfe_u32 s16, s16, 0x2000d
	s_add_i32 s16, s3, s16
	s_bfe_i32 s18, s16, 0x80000
	s_and_b32 s16, s16, 0xfc
	s_sub_i32 s3, s3, s16
	s_sext_i32_i16 s18, s18
	s_sext_i32_i8 s3, s3
	s_add_i32 s16, s17, s3
	s_ashr_i32 s18, s18, 2
